# FFN k-loop with single staging set (prefetch distance 1)
# speedup vs baseline: 1.0651x; 1.0077x over previous
.LBB0_669:
	s_or_b64 exec, exec, s[18:19]
	v_add_co_u32_e32 v4, vcc, 0x7000, v30
	s_mul_i32 s18, s52, 62
	s_nop 0
	v_addc_co_u32_e32 v5, vcc, 0, v31, vcc
	global_load_dwordx4 v[110:113], v[4:5], off
	v_ashrrev_i32_e32 v4, 3, v41
	s_add_i32 s18, s3, s18
	v_lshrrev_b32_e32 v116, 4, v4
	s_add_i32 s18, s18, s51
	v_ashrrev_i32_e32 v8, 3, v40
	v_lshlrev_b64 v[4:5], 18, v[116:117]
	s_lshl_b32 s18, s18, 1
	v_lshl_add_u64 v[2:3], v[2:3], 1, v[4:5]
	v_lshrrev_b32_e32 v116, 4, v8
	v_subrev_u16_e32 v4, s18, v163
	v_ashrrev_i32_e32 v7, 3, v39
	v_lshl_add_u64 v[128:129], v[122:123], 0, v[2:3]
	v_lshlrev_b64 v[2:3], 18, v[116:117]
	v_and_b32_e32 v4, 0x7f, v4
	s_waitcnt lgkmcnt(0)
	s_barrier
	ds_read_b128 v[102:105], v168 offset:18432
	ds_read_b128 v[94:97], v168 offset:23040
	ds_read_b128 v[106:109], v169
	ds_read_b128 v[98:101], v169 offset:4608
	v_lshl_or_b32 v2, v4, 7, v2
	v_lshrrev_b32_e32 v116, 4, v7
	v_subrev_u16_e32 v4, s18, v164
	v_ashrrev_i32_e32 v6, 3, v38
	v_lshl_add_u64 v[130:131], v[122:123], 0, v[2:3]
	v_lshlrev_b64 v[2:3], 18, v[116:117]
	v_and_b32_e32 v4, 0x7f, v4
	v_lshl_or_b32 v2, v4, 7, v2
	v_lshrrev_b32_e32 v116, 4, v6
	v_subrev_u16_e32 v4, s18, v165
	v_lshl_add_u64 v[132:133], v[122:123], 0, v[2:3]
	v_lshlrev_b64 v[2:3], 18, v[116:117]
	v_and_b32_e32 v4, 0x7f, v4
	v_lshl_or_b32 v2, v4, 7, v2
	v_lshl_add_u64 v[134:135], v[122:123], 0, v[2:3]
	v_mov_b32_e32 v2, 0
	s_mov_b32 s15, 0
	v_lshl_add_u64 v[136:137], v[124:125], 0, s[16:17]
	s_mov_b64 s[16:17], 0
	v_mov_b32_e32 v3, v2
	v_mov_b32_e32 v4, v2
	v_mov_b32_e32 v5, v2
	v_mov_b32_e32 v6, v2
	v_mov_b32_e32 v7, v2
	v_mov_b32_e32 v8, v2
	v_mov_b32_e32 v9, v2
	v_mov_b32_e32 v10, v2
	v_mov_b32_e32 v11, v2
	v_mov_b32_e32 v12, v2
	v_mov_b32_e32 v13, v2
	v_mov_b32_e32 v14, v2
	v_mov_b32_e32 v15, v2
	v_mov_b32_e32 v16, v2
	v_mov_b32_e32 v17, v2
	v_mov_b32_e32 v18, v2
	v_mov_b32_e32 v19, v2
	v_mov_b32_e32 v20, v2
	v_mov_b32_e32 v21, v2
	v_mov_b32_e32 v22, v2
	v_mov_b32_e32 v23, v2
	v_mov_b32_e32 v24, v2
	v_mov_b32_e32 v25, v2
	v_mov_b32_e32 v26, v2
	v_mov_b32_e32 v27, v2
	v_mov_b32_e32 v28, v2
	v_mov_b32_e32 v29, v2
	v_mov_b32_e32 v30, v2
	v_mov_b32_e32 v31, v2
	v_mov_b32_e32 v32, v2
	v_mov_b32_e32 v33, v2
	v_mov_b32_e32 v34, v2
	v_mov_b32_e32 v35, v2
	v_mov_b32_e32 v36, v2
	v_mov_b32_e32 v37, v2
	v_mov_b32_e32 v38, v2
	v_mov_b32_e32 v39, v2
	v_mov_b32_e32 v40, v2
	v_mov_b32_e32 v41, v2
	v_mov_b32_e32 v42, v2
	v_mov_b32_e32 v43, v2
	v_mov_b32_e32 v44, v2
	v_mov_b32_e32 v45, v2
	v_mov_b32_e32 v46, v2
	v_mov_b32_e32 v47, v2
	v_mov_b32_e32 v48, v2
	v_mov_b32_e32 v49, v2
	v_mov_b32_e32 v50, v2
	v_mov_b32_e32 v51, v2
	v_mov_b32_e32 v52, v2
	v_mov_b32_e32 v53, v2
	v_mov_b32_e32 v54, v2
	v_mov_b32_e32 v55, v2
	v_mov_b32_e32 v56, v2
	v_mov_b32_e32 v57, v2
	v_mov_b32_e32 v58, v2
	v_mov_b32_e32 v59, v2
	v_mov_b32_e32 v60, v2
	v_mov_b32_e32 v61, v2
	v_mov_b32_e32 v62, v2
	v_mov_b32_e32 v63, v2
	v_mov_b32_e32 v64, v2
	v_mov_b32_e32 v65, v2
	s_mov_b32 s63, 0
	s_mov_b32 s62, 0x102c000
	v_lshl_add_u64 v[220:221], v[136:137], 0, s[62:63]
	s_mov_b32 s62, 0x102d000
	v_lshl_add_u64 v[222:223], v[136:137], 0, s[62:63]
	s_mov_b32 s62, 0x102e000
	v_lshl_add_u64 v[224:225], v[136:137], 0, s[62:63]
	s_mov_b32 s62, 0x102f000
	v_lshl_add_u64 v[226:227], v[136:137], 0, s[62:63]
	s_mov_b32 s64, 0
	s_mov_b32 s65, 0
	s_mov_b32 s66, 7
.Lk5_loop:
	ds_read_b128 v[172:175], v168 offset:18464
	ds_read_b128 v[176:179], v168 offset:23072
	ds_read_b128 v[180:183], v169 offset:32
	ds_read_b128 v[184:187], v169 offset:4640
	s_waitcnt lgkmcnt(4)
	v_mfma_f32_32x32x16_bf16 v[50:65], v[102:105], v[106:109], v[50:65]
	s_waitcnt vmcnt(7)
	ds_write_b128 v140, v[66:69] offset:36864
	v_mfma_f32_32x32x16_bf16 v[34:49], v[94:97], v[106:109], v[34:49]
	s_waitcnt vmcnt(6)
	ds_write_b128 v140, v[74:77] offset:55296
	v_mfma_f32_32x32x16_bf16 v[18:33], v[102:105], v[98:101], v[18:33]
	s_waitcnt vmcnt(5)
	ds_write_b128 v142, v[70:73] offset:36864
	v_mfma_f32_32x32x16_bf16 v[2:17], v[94:97], v[98:101], v[2:17]
	s_waitcnt vmcnt(4)
	ds_write_b128 v142, v[82:85] offset:55296
	ds_read_b128 v[102:105], v168 offset:18496
	ds_read_b128 v[94:97], v168 offset:23104
	ds_read_b128 v[106:109], v169 offset:64
	ds_read_b128 v[98:101], v169 offset:4672
	s_waitcnt lgkmcnt(4)
	v_mfma_f32_32x32x16_bf16 v[50:65], v[172:175], v[180:183], v[50:65]
	s_waitcnt vmcnt(3)
	ds_write_b128 v144, v[78:81] offset:36864
	v_mfma_f32_32x32x16_bf16 v[34:49], v[176:179], v[180:183], v[34:49]
	s_waitcnt vmcnt(2)
	ds_write_b128 v144, v[86:89] offset:55296
	v_mfma_f32_32x32x16_bf16 v[18:33], v[172:175], v[184:187], v[18:33]
	s_waitcnt vmcnt(1)
	ds_write_b128 v146, v[90:93] offset:36864
	v_mfma_f32_32x32x16_bf16 v[2:17], v[176:179], v[184:187], v[2:17]
	s_waitcnt vmcnt(0)
	ds_write_b128 v146, v[110:113] offset:55296
	ds_read_b128 v[172:175], v168 offset:18528
	ds_read_b128 v[176:179], v168 offset:23136
	ds_read_b128 v[180:183], v169 offset:96
	ds_read_b128 v[184:187], v169 offset:4704
	s_waitcnt lgkmcnt(8)
	v_mfma_f32_32x32x16_bf16 v[50:65], v[102:105], v[106:109], v[50:65]
	s_mov_b64 exec, s[4:5]
	v_lshl_add_u64 v[66:67], v[134:135], 0, s[64:65]
	global_load_dwordx4 v[66:69], v[66:67], off
	s_mov_b64 exec, -1
	v_lshl_add_u64 v[74:75], v[220:221], 0, s[64:65]
	global_load_dwordx4 v[74:77], v[74:75], off
	v_mfma_f32_32x32x16_bf16 v[34:49], v[94:97], v[106:109], v[34:49]
	s_mov_b64 exec, s[6:7]
	v_lshl_add_u64 v[70:71], v[132:133], 0, s[64:65]
	global_load_dwordx4 v[70:73], v[70:71], off
	s_mov_b64 exec, -1
	v_lshl_add_u64 v[82:83], v[222:223], 0, s[64:65]
	global_load_dwordx4 v[82:85], v[82:83], off
	v_mfma_f32_32x32x16_bf16 v[18:33], v[102:105], v[98:101], v[18:33]
	s_mov_b64 exec, s[8:9]
	v_lshl_add_u64 v[78:79], v[130:131], 0, s[64:65]
	global_load_dwordx4 v[78:81], v[78:79], off
	s_mov_b64 exec, -1
	v_lshl_add_u64 v[86:87], v[224:225], 0, s[64:65]
	global_load_dwordx4 v[86:89], v[86:87], off
	v_mfma_f32_32x32x16_bf16 v[2:17], v[94:97], v[98:101], v[2:17]
	s_mov_b64 exec, s[10:11]
	v_lshl_add_u64 v[90:91], v[128:129], 0, s[64:65]
	global_load_dwordx4 v[90:93], v[90:91], off
	s_mov_b64 exec, -1
	v_lshl_add_u64 v[110:111], v[226:227], 0, s[64:65]
	global_load_dwordx4 v[110:113], v[110:111], off
	s_add_u32 s64, s64, 0x4000
	s_addc_u32 s65, s65, 0
	s_waitcnt lgkmcnt(0)
	s_barrier
	ds_read_b128 v[102:105], v168 offset:55296
	ds_read_b128 v[94:97], v168 offset:59904
	ds_read_b128 v[106:109], v169 offset:36864
	ds_read_b128 v[98:101], v169 offset:41472
	v_mfma_f32_32x32x16_bf16 v[50:65], v[172:175], v[180:183], v[50:65]
	v_mfma_f32_32x32x16_bf16 v[34:49], v[176:179], v[180:183], v[34:49]
	v_mfma_f32_32x32x16_bf16 v[18:33], v[172:175], v[184:187], v[18:33]
	v_mfma_f32_32x32x16_bf16 v[2:17], v[176:179], v[184:187], v[2:17]
	ds_read_b128 v[172:175], v168 offset:55328
	ds_read_b128 v[176:179], v168 offset:59936
	ds_read_b128 v[180:183], v169 offset:36896
	ds_read_b128 v[184:187], v169 offset:41504
	s_waitcnt lgkmcnt(4)
	v_mfma_f32_32x32x16_bf16 v[50:65], v[102:105], v[106:109], v[50:65]
	s_waitcnt vmcnt(7)
	ds_write_b128 v140, v[66:69]
	v_mfma_f32_32x32x16_bf16 v[34:49], v[94:97], v[106:109], v[34:49]
	s_waitcnt vmcnt(6)
	ds_write_b128 v140, v[74:77] offset:18432
	v_mfma_f32_32x32x16_bf16 v[18:33], v[102:105], v[98:101], v[18:33]
	s_waitcnt vmcnt(5)
	ds_write_b128 v142, v[70:73]
	v_mfma_f32_32x32x16_bf16 v[2:17], v[94:97], v[98:101], v[2:17]
	s_waitcnt vmcnt(4)
	ds_write_b128 v142, v[82:85] offset:18432
	ds_read_b128 v[102:105], v168 offset:55360
	ds_read_b128 v[94:97], v168 offset:59968
	ds_read_b128 v[106:109], v169 offset:36928
	ds_read_b128 v[98:101], v169 offset:41536
	s_waitcnt lgkmcnt(4)
	v_mfma_f32_32x32x16_bf16 v[50:65], v[172:175], v[180:183], v[50:65]
	s_waitcnt vmcnt(3)
	ds_write_b128 v144, v[78:81]
	v_mfma_f32_32x32x16_bf16 v[34:49], v[176:179], v[180:183], v[34:49]
	s_waitcnt vmcnt(2)
	ds_write_b128 v144, v[86:89] offset:18432
	v_mfma_f32_32x32x16_bf16 v[18:33], v[172:175], v[184:187], v[18:33]
	s_waitcnt vmcnt(1)
	ds_write_b128 v146, v[90:93]
	v_mfma_f32_32x32x16_bf16 v[2:17], v[176:179], v[184:187], v[2:17]
	s_waitcnt vmcnt(0)
	ds_write_b128 v146, v[110:113] offset:18432
	ds_read_b128 v[172:175], v168 offset:55392
	ds_read_b128 v[176:179], v168 offset:60000
	ds_read_b128 v[180:183], v169 offset:36960
	ds_read_b128 v[184:187], v169 offset:41568
	s_waitcnt lgkmcnt(8)
	v_mfma_f32_32x32x16_bf16 v[50:65], v[102:105], v[106:109], v[50:65]
	s_mov_b64 exec, s[4:5]
	v_lshl_add_u64 v[66:67], v[134:135], 0, s[64:65]
	global_load_dwordx4 v[66:69], v[66:67], off
	s_mov_b64 exec, -1
	v_lshl_add_u64 v[74:75], v[220:221], 0, s[64:65]
	global_load_dwordx4 v[74:77], v[74:75], off
	v_mfma_f32_32x32x16_bf16 v[34:49], v[94:97], v[106:109], v[34:49]
	s_mov_b64 exec, s[6:7]
	v_lshl_add_u64 v[70:71], v[132:133], 0, s[64:65]
	global_load_dwordx4 v[70:73], v[70:71], off
	s_mov_b64 exec, -1
	v_lshl_add_u64 v[82:83], v[222:223], 0, s[64:65]
	global_load_dwordx4 v[82:85], v[82:83], off
	v_mfma_f32_32x32x16_bf16 v[18:33], v[102:105], v[98:101], v[18:33]
	s_mov_b64 exec, s[8:9]
	v_lshl_add_u64 v[78:79], v[130:131], 0, s[64:65]
	global_load_dwordx4 v[78:81], v[78:79], off
	s_mov_b64 exec, -1
	v_lshl_add_u64 v[86:87], v[224:225], 0, s[64:65]
	global_load_dwordx4 v[86:89], v[86:87], off
	v_mfma_f32_32x32x16_bf16 v[2:17], v[94:97], v[98:101], v[2:17]
	s_mov_b64 exec, s[10:11]
	v_lshl_add_u64 v[90:91], v[128:129], 0, s[64:65]
	global_load_dwordx4 v[90:93], v[90:91], off
	s_mov_b64 exec, -1
	v_lshl_add_u64 v[110:111], v[226:227], 0, s[64:65]
	global_load_dwordx4 v[110:113], v[110:111], off
	s_add_u32 s64, s64, 0x4000
	s_addc_u32 s65, s65, 0
	s_waitcnt lgkmcnt(0)
	s_barrier
	ds_read_b128 v[102:105], v168 offset:18432
	ds_read_b128 v[94:97], v168 offset:23040
	ds_read_b128 v[106:109], v169
	ds_read_b128 v[98:101], v169 offset:4608
	v_mfma_f32_32x32x16_bf16 v[50:65], v[172:175], v[180:183], v[50:65]
	v_mfma_f32_32x32x16_bf16 v[34:49], v[176:179], v[180:183], v[34:49]
	v_mfma_f32_32x32x16_bf16 v[18:33], v[172:175], v[184:187], v[18:33]
	v_mfma_f32_32x32x16_bf16 v[2:17], v[176:179], v[184:187], v[2:17]
	s_sub_u32 s66, s66, 1
	s_cmp_lg_u32 s66, 0
	s_cbranch_scc1 .Lk5_loop
	s_branch .LBB0_679

.LBB0_2386:
	s_or_b64 exec, exec, s[22:23]
	v_add_co_u32_e32 v4, vcc, 0x7000, v30
	s_mul_i32 s22, s38, 62
	s_nop 0
	v_addc_co_u32_e32 v5, vcc, 0, v31, vcc
	global_load_dwordx4 v[110:113], v[4:5], off
	v_ashrrev_i32_e32 v4, 3, v41
	s_add_i32 s22, s24, s22
	v_lshrrev_b32_e32 v116, 4, v4
	s_add_i32 s22, s22, s37
	v_ashrrev_i32_e32 v8, 3, v40
	v_lshlrev_b64 v[4:5], 18, v[116:117]
	s_lshl_b32 s22, s22, 1
	v_lshl_add_u64 v[2:3], v[2:3], 1, v[4:5]
	v_lshrrev_b32_e32 v116, 4, v8
	v_subrev_u16_e32 v4, s22, v163
	v_ashrrev_i32_e32 v7, 3, v39
	v_lshl_add_u64 v[128:129], v[122:123], 0, v[2:3]
	v_lshlrev_b64 v[2:3], 18, v[116:117]
	v_and_b32_e32 v4, 0x7f, v4
	s_waitcnt lgkmcnt(0)
	s_barrier
	ds_read_b128 v[102:105], v168 offset:18432
	ds_read_b128 v[94:97], v168 offset:23040
	ds_read_b128 v[106:109], v169
	ds_read_b128 v[98:101], v169 offset:4608
	v_lshl_or_b32 v2, v4, 7, v2
	v_lshrrev_b32_e32 v116, 4, v7
	v_subrev_u16_e32 v4, s22, v164
	v_ashrrev_i32_e32 v6, 3, v38
	v_lshl_add_u64 v[130:131], v[122:123], 0, v[2:3]
	v_lshlrev_b64 v[2:3], 18, v[116:117]
	v_and_b32_e32 v4, 0x7f, v4
	v_lshl_or_b32 v2, v4, 7, v2
	v_lshrrev_b32_e32 v116, 4, v6
	v_subrev_u16_e32 v4, s22, v165
	v_lshl_add_u64 v[132:133], v[122:123], 0, v[2:3]
	v_lshlrev_b64 v[2:3], 18, v[116:117]
	v_and_b32_e32 v4, 0x7f, v4
	v_lshl_or_b32 v2, v4, 7, v2
	v_lshl_add_u64 v[134:135], v[122:123], 0, v[2:3]
	v_mov_b32_e32 v2, 0
	s_mov_b32 s19, 0
	v_lshl_add_u64 v[136:137], v[124:125], 0, s[20:21]
	s_mov_b64 s[20:21], 0
	v_mov_b32_e32 v3, v2
	v_mov_b32_e32 v4, v2
	v_mov_b32_e32 v5, v2
	v_mov_b32_e32 v6, v2
	v_mov_b32_e32 v7, v2
	v_mov_b32_e32 v8, v2
	v_mov_b32_e32 v9, v2
	v_mov_b32_e32 v10, v2
	v_mov_b32_e32 v11, v2
	v_mov_b32_e32 v12, v2
	v_mov_b32_e32 v13, v2
	v_mov_b32_e32 v14, v2
	v_mov_b32_e32 v15, v2
	v_mov_b32_e32 v16, v2
	v_mov_b32_e32 v17, v2
	v_mov_b32_e32 v18, v2
	v_mov_b32_e32 v19, v2
	v_mov_b32_e32 v20, v2
	v_mov_b32_e32 v21, v2
	v_mov_b32_e32 v22, v2
	v_mov_b32_e32 v23, v2
	v_mov_b32_e32 v24, v2
	v_mov_b32_e32 v25, v2
	v_mov_b32_e32 v26, v2
	v_mov_b32_e32 v27, v2
	v_mov_b32_e32 v28, v2
	v_mov_b32_e32 v29, v2
	v_mov_b32_e32 v30, v2
	v_mov_b32_e32 v31, v2
	v_mov_b32_e32 v32, v2
	v_mov_b32_e32 v33, v2
	v_mov_b32_e32 v34, v2
	v_mov_b32_e32 v35, v2
	v_mov_b32_e32 v36, v2
	v_mov_b32_e32 v37, v2
	v_mov_b32_e32 v38, v2
	v_mov_b32_e32 v39, v2
	v_mov_b32_e32 v40, v2
	v_mov_b32_e32 v41, v2
	v_mov_b32_e32 v42, v2
	v_mov_b32_e32 v43, v2
	v_mov_b32_e32 v44, v2
	v_mov_b32_e32 v45, v2
	v_mov_b32_e32 v46, v2
	v_mov_b32_e32 v47, v2
	v_mov_b32_e32 v48, v2
	v_mov_b32_e32 v49, v2
	v_mov_b32_e32 v50, v2
	v_mov_b32_e32 v51, v2
	v_mov_b32_e32 v52, v2
	v_mov_b32_e32 v53, v2
	v_mov_b32_e32 v54, v2
	v_mov_b32_e32 v55, v2
	v_mov_b32_e32 v56, v2
	v_mov_b32_e32 v57, v2
	v_mov_b32_e32 v58, v2
	v_mov_b32_e32 v59, v2
	v_mov_b32_e32 v60, v2
	v_mov_b32_e32 v61, v2
	v_mov_b32_e32 v62, v2
	v_mov_b32_e32 v63, v2
	v_mov_b32_e32 v64, v2
	v_mov_b32_e32 v65, v2
	s_mov_b32 s63, 0
	s_mov_b32 s62, 0x1b2c000
	v_lshl_add_u64 v[220:221], v[136:137], 0, s[62:63]
	s_mov_b32 s62, 0x1b2d000
	v_lshl_add_u64 v[222:223], v[136:137], 0, s[62:63]
	s_mov_b32 s62, 0x1b2e000
	v_lshl_add_u64 v[224:225], v[136:137], 0, s[62:63]
	s_mov_b32 s62, 0x1b2f000
	v_lshl_add_u64 v[226:227], v[136:137], 0, s[62:63]
	s_mov_b32 s64, 0
	s_mov_b32 s65, 0
	s_mov_b32 s66, 7
